# thr radix-select digit scan rewritten bank-conflict-free: thread = (query, 16-bin group), wave totals through an LDS scratch
# speedup vs baseline: 1.0324x; 1.0169x over previous
; DI void dsa_thr_item(const Params& p, int b, int qblk, char* smem) {
;     ...
; #pragma unroll 1
;     for (int qq = 0; qq < 4; ++qq) {
;       const int q = wave * 4 + qq;
;       const int rk = rank[q];
;       int c[4];
; #pragma unroll
;       for (int j = 0; j < 4; ++j) c[j] = (int)hist[(255 - 4 * lane - j) * 32 + q];
;       int s = c[0] + c[1] + c[2] + c[3];
;       int P = wave_incl_scan(s, lane);
;       int excl = P - s;
;       if (P >= rk && excl < rk) {
;         int cum = excl; int bin = 0; int nr = 1; bool found = false;
; #pragma unroll
;         for (int j = 0; j < 4; ++j) {
;           if (!found && cum + c[j] >= rk) { bin = 255 - 4 * lane - j; nr = rk - cum; found = true; }
;           if (!found) cum += c[j];
;         }
;         pref[q] = (pref[q] << 8) | (unsigned)bin;
;         rank[q] = nr;
;       }
;     }
.LBB0_334:
	s_or_b64 exec, exec, s[54:55]
	s_mov_b32 s58, 0
	s_waitcnt lgkmcnt(0)
	s_barrier
	v_readfirstlane_b32 s58, v167
	v_and_b32_e32 v28, 31, v177
	v_lshlrev_b32_e32 v28, 2, v28
	v_lshrrev_b32_e32 v29, 5, v177
	v_lshl_add_u32 v29, v167, 1, v29
	v_lshlrev_b32_e32 v27, 4, v29
	v_sub_u32_e32 v27, 0xff, v27
	v_lshlrev_b32_e32 v19, 11, v29
	v_sub_u32_e32 v19, 0x7800, v19
	v_add_u32_e32 v19, v19, v28
	ds_read_b32 v0, v19 offset:1920
	ds_read_b32 v1, v19 offset:1792
	ds_read_b32 v2, v19 offset:1664
	ds_read_b32 v3, v19 offset:1536
	ds_read_b32 v4, v19 offset:1408
	ds_read_b32 v5, v19 offset:1280
	ds_read_b32 v6, v19 offset:1152
	ds_read_b32 v7, v19 offset:1024
	ds_read_b32 v8, v19 offset:896
	ds_read_b32 v9, v19 offset:768
	ds_read_b32 v10, v19 offset:640
	ds_read_b32 v11, v19 offset:512
	ds_read_b32 v12, v19 offset:384
	ds_read_b32 v13, v19 offset:256
	ds_read_b32 v14, v19 offset:128
	ds_read_b32 v15, v19 offset:0
	v_add_u32_e32 v21, 0x8000, v28
	ds_read_b32 v22, v21 offset:128
	ds_read_b32 v23, v21
	s_mov_b32 s60, 0
	s_mov_b32 s61, -1
	s_mov_b32 s62, -1
	s_mov_b32 s63, 0
	s_waitcnt lgkmcnt(0)
	v_add3_u32 v16, v0, v1, v2
	v_add3_u32 v17, v3, v4, v5
	v_add3_u32 v18, v6, v7, v8
	v_add3_u32 v29, v9, v10, v11
	v_add3_u32 v16, v16, v17, v18
	v_add3_u32 v29, v29, v12, v13
	v_add3_u32 v16, v16, v14, v15
	v_add_u32_e32 v16, v16, v29
	v_mov_b32_e32 v17, v16
	v_mov_b32_e32 v18, v16
	s_nop 1
	v_permlane32_swap_b32_e32 v17, v18
	v_lshlrev_b32_e32 v20, 7, v167
	v_add_u32_e32 v20, v20, v28
	v_add_u32_e32 v20, 0x10000, v20
	v_add_u32_e32 v29, v16, v18
	s_and_saveexec_b64 s[64:65], s[62:63]
	ds_write_b32 v20, v29
	s_mov_b64 exec, s[64:65]
	v_add_u32_e32 v21, 0x10000, v28
	s_waitcnt lgkmcnt(0)
	s_barrier
	ds_read_b32 v30, v21 offset:0
	ds_read_b32 v31, v21 offset:128
	ds_read_b32 v32, v21 offset:256
	ds_read_b32 v33, v21 offset:384
	ds_read_b32 v34, v21 offset:512
	ds_read_b32 v35, v21 offset:640
	ds_read_b32 v36, v21 offset:768
	v_cndmask_b32_e64 v24, 0, v17, s[60:61]
	s_waitcnt lgkmcnt(0)
	s_cmp_gt_u32 s58, 0
	s_cselect_b32 s74, -1, 0
	v_and_b32_e32 v30, s74, v30
	v_add_u32_e32 v24, v24, v30
	s_cmp_gt_u32 s58, 1
	s_cselect_b32 s74, -1, 0
	v_and_b32_e32 v31, s74, v31
	v_add_u32_e32 v24, v24, v31
	s_cmp_gt_u32 s58, 2
	s_cselect_b32 s74, -1, 0
	v_and_b32_e32 v32, s74, v32
	v_add_u32_e32 v24, v24, v32
	s_cmp_gt_u32 s58, 3
	s_cselect_b32 s74, -1, 0
	v_and_b32_e32 v33, s74, v33
	v_add_u32_e32 v24, v24, v33
	s_cmp_gt_u32 s58, 4
	s_cselect_b32 s74, -1, 0
	v_and_b32_e32 v34, s74, v34
	v_add_u32_e32 v24, v24, v34
	s_cmp_gt_u32 s58, 5
	s_cselect_b32 s74, -1, 0
	v_and_b32_e32 v35, s74, v35
	v_add_u32_e32 v24, v24, v35
	s_cmp_gt_u32 s58, 6
	s_cselect_b32 s74, -1, 0
	v_and_b32_e32 v36, s74, v36
	v_add_u32_e32 v24, v24, v36
	v_mov_b32_e32 v25, 0
	v_mov_b32_e32 v26, v24
	v_add_u32_e32 v0, v24, v0
	v_add_u32_e32 v1, v0, v1
	v_add_u32_e32 v2, v1, v2
	v_add_u32_e32 v3, v2, v3
	v_add_u32_e32 v4, v3, v4
	v_add_u32_e32 v5, v4, v5
	v_add_u32_e32 v6, v5, v6
	v_add_u32_e32 v7, v6, v7
	v_add_u32_e32 v8, v7, v8
	v_add_u32_e32 v9, v8, v9
	v_add_u32_e32 v10, v9, v10
	v_add_u32_e32 v11, v10, v11
	v_add_u32_e32 v12, v11, v12
	v_add_u32_e32 v13, v12, v13
	v_add_u32_e32 v14, v13, v14
	v_add_u32_e32 v15, v14, v15
	v_cmp_gt_i32_e64 s[0:1], v22, v0
	v_cmp_gt_i32_e64 s[6:7], v22, v1
	v_cmp_gt_i32_e64 s[8:9], v22, v2
	v_cmp_gt_i32_e64 s[10:11], v22, v3
	v_addc_co_u32_e64 v25, s[12:13], v25, 0, s[0:1]
	v_cndmask_b32_e64 v26, v26, v0, s[0:1]
	v_addc_co_u32_e64 v25, s[12:13], v25, 0, s[6:7]
	v_cndmask_b32_e64 v26, v26, v1, s[6:7]
	v_addc_co_u32_e64 v25, s[12:13], v25, 0, s[8:9]
	v_cndmask_b32_e64 v26, v26, v2, s[8:9]
	v_addc_co_u32_e64 v25, s[12:13], v25, 0, s[10:11]
	v_cndmask_b32_e64 v26, v26, v3, s[10:11]
	v_cmp_gt_i32_e64 s[0:1], v22, v4
	v_cmp_gt_i32_e64 s[6:7], v22, v5
	v_cmp_gt_i32_e64 s[8:9], v22, v6
	v_cmp_gt_i32_e64 s[10:11], v22, v7
	v_addc_co_u32_e64 v25, s[12:13], v25, 0, s[0:1]
	v_cndmask_b32_e64 v26, v26, v4, s[0:1]
	v_addc_co_u32_e64 v25, s[12:13], v25, 0, s[6:7]
	v_cndmask_b32_e64 v26, v26, v5, s[6:7]
	v_addc_co_u32_e64 v25, s[12:13], v25, 0, s[8:9]
	v_cndmask_b32_e64 v26, v26, v6, s[8:9]
	v_addc_co_u32_e64 v25, s[12:13], v25, 0, s[10:11]
	v_cndmask_b32_e64 v26, v26, v7, s[10:11]
	v_cmp_gt_i32_e64 s[0:1], v22, v8
	v_cmp_gt_i32_e64 s[6:7], v22, v9
	v_cmp_gt_i32_e64 s[8:9], v22, v10
	v_cmp_gt_i32_e64 s[10:11], v22, v11
	v_addc_co_u32_e64 v25, s[12:13], v25, 0, s[0:1]
	v_cndmask_b32_e64 v26, v26, v8, s[0:1]
	v_addc_co_u32_e64 v25, s[12:13], v25, 0, s[6:7]
	v_cndmask_b32_e64 v26, v26, v9, s[6:7]
	v_addc_co_u32_e64 v25, s[12:13], v25, 0, s[8:9]
	v_cndmask_b32_e64 v26, v26, v10, s[8:9]
	v_addc_co_u32_e64 v25, s[12:13], v25, 0, s[10:11]
	v_cndmask_b32_e64 v26, v26, v11, s[10:11]
	v_cmp_gt_i32_e64 s[0:1], v22, v12
	v_cmp_gt_i32_e64 s[6:7], v22, v13
	v_cmp_gt_i32_e64 s[8:9], v22, v14
	v_cmp_gt_i32_e64 s[10:11], v22, v15
	v_addc_co_u32_e64 v25, s[12:13], v25, 0, s[0:1]
	v_cndmask_b32_e64 v26, v26, v12, s[0:1]
	v_addc_co_u32_e64 v25, s[12:13], v25, 0, s[6:7]
	v_cndmask_b32_e64 v26, v26, v13, s[6:7]
	v_addc_co_u32_e64 v25, s[12:13], v25, 0, s[8:9]
	v_cndmask_b32_e64 v26, v26, v14, s[8:9]
	v_addc_co_u32_e64 v25, s[12:13], v25, 0, s[10:11]
	v_cndmask_b32_e64 v26, v26, v15, s[10:11]
	v_cmp_gt_i32_e64 s[0:1], v22, v24
	v_cmp_ge_i32_e64 s[6:7], v15, v22
	v_sub_u32_e32 v27, v27, v25
	v_sub_u32_e32 v26, v22, v26
	v_lshl_or_b32 v23, v23, 8, v27
	v_add_u32_e32 v21, 0x8000, v28
	s_and_b64 s[0:1], s[0:1], s[6:7]
	s_and_saveexec_b64 s[64:65], s[0:1]
	ds_write2_b32 v21, v23, v26 offset1:32
	s_mov_b64 exec, s[64:65]
	s_branch .LBB0_262
